# lever 1: counted vmcnt ladder in the gain-less convT instances (convert+LDS-write element i as soon as load i returns)
# speedup vs baseline: 1.0023x; 1.0019x over previous
; template <class F>
; DI void convT(bf16* dst, int N, int K, const float* src, const float* src2, int ld, const float* gain, F cmap, bf16* tile) {
;     ...
;     for (int e = tid; e < 4096; e += NTHR) {
;       const int kk = e >> 6, nn = e & 63;
;       const int k = tk * 64 + kk, n = tn * 64 + nn;
;       const int sc = cmap(n);
;       float v = 0.f;
;       if (sc >= 0) {
;         const float* s = (sc & (1 << 28)) ? src2 : src;
;         v = s[(size_t)k * ld + (sc & ((1 << 28) - 1))];
;         if (gain) v *= gain[k];
;       }
;       tile[nn * 66 + kk] = f2bf(v);
.Lcvb5_e:
	v_lshl_add_u32 v7, v7, 1, v17
	s_waitcnt vmcnt(7)
	v_cvt_pk_bf16_f32 v230, v230, s0
	ds_write_b16 v7, v230
	s_waitcnt vmcnt(6)
	v_cvt_pk_bf16_f32 v231, v231, s0
	ds_write_b16 v7, v231 offset:16
	s_waitcnt vmcnt(5)
	v_cvt_pk_bf16_f32 v232, v232, s0
	ds_write_b16 v7, v232 offset:32
	s_waitcnt vmcnt(4)
	v_cvt_pk_bf16_f32 v233, v233, s0
	ds_write_b16 v7, v233 offset:48
	s_waitcnt vmcnt(3)
	v_cvt_pk_bf16_f32 v234, v234, s0
	ds_write_b16 v7, v234 offset:64
	s_waitcnt vmcnt(2)
	v_cvt_pk_bf16_f32 v235, v235, s0
	ds_write_b16 v7, v235 offset:80
	s_waitcnt vmcnt(1)
	v_cvt_pk_bf16_f32 v236, v236, s0
	ds_write_b16 v7, v236 offset:96
	s_waitcnt vmcnt(0)
	v_cvt_pk_bf16_f32 v237, v237, s0
	ds_write_b16 v7, v237 offset:112
